# baseline (speedup 1.0000x reference)
; __device__ __forceinline__ void partialSM(f32x16& p0, f32x16& p1, float& m_reg, float& mn, float& alpha) {
;     float pmax = p0[0];
; #pragma unroll
;     for (int r = 1; r < 16; ++r) pmax = fmaxf(pmax, p0[r]);
; #pragma unroll
;     for (int r = 0; r < 16; ++r) pmax = fmaxf(pmax, p1[r]);
;     { auto rr = __builtin_amdgcn_permlane32_swap(__float_as_uint(pmax), __float_as_uint(pmax), false, false);
;       pmax = fmaxf(__uint_as_float(rr[0]), __uint_as_float(rr[1])); }
;     constexpr float C2 = 1.4426950408889634f * ASCALE;
;     if (__builtin_expect(__all((pmax - m_reg) * ASCALE <= ATHR), 1)) { mn = m_reg; alpha = 1.f; }
;     else { mn = fmaxf(m_reg, pmax); alpha = __builtin_amdgcn_exp2f((m_reg - mn) * C2); m_reg = mn; }
.LBB0_410:
	s_nop 0
	s_waitcnt lgkmcnt(4)
	v_mfma_f32_32x32x16_bf16 v[50:65], v[166:169], v[214:217], v[50:65]
	ds_read_b64_tr_b16 v[214:215], v194 offset:0x200
	ds_read_b64_tr_b16 v[216:217], v194 offset:0xa00
	v_max_f32_e32 v0, v82, v83
	v_mfma_f32_32x32x16_bf16 v[50:65], v[170:173], v[218:221], v[50:65]
	ds_read_b64_tr_b16 v[218:219], v194 offset:0x1200
	ds_read_b64_tr_b16 v[220:221], v194 offset:0x1a00
	v_max3_f32 v0, v0, v84, v85
	v_max3_f32 v0, v0, v86, v87
	s_waitcnt lgkmcnt(4)
	v_mfma_f32_32x32x16_bf16 v[50:65], v[174:177], v[222:225], v[50:65]
	ds_read_b64_tr_b16 v[222:223], v194 offset:0x2200
	ds_read_b64_tr_b16 v[224:225], v194 offset:0x2a00
	v_max3_f32 v0, v0, v88, v89
	v_max3_f32 v0, v0, v90, v91
	v_mfma_f32_32x32x16_bf16 v[50:65], v[178:181], v[226:229], v[50:65]
	ds_read_b64_tr_b16 v[226:227], v194 offset:0x3200
	ds_read_b64_tr_b16 v[228:229], v194 offset:0x3a00
	v_max3_f32 v0, v0, v92, v93
	v_max3_f32 v0, v0, v94, v95
	v_max3_f32 v0, v0, v96, v97
	s_waitcnt lgkmcnt(4)
	v_mfma_f32_32x32x16_bf16 v[34:49], v[166:169], v[214:217], v[34:49]
	ds_read_b64_tr_b16 v[214:215], v194 offset:0x400
	ds_read_b64_tr_b16 v[216:217], v194 offset:0xc00
	v_max3_f32 v0, v0, v66, v67
	v_max3_f32 v0, v0, v68, v69
	v_mfma_f32_32x32x16_bf16 v[34:49], v[170:173], v[218:221], v[34:49]
	ds_read_b64_tr_b16 v[218:219], v194 offset:0x1400
	ds_read_b64_tr_b16 v[220:221], v194 offset:0x1c00
	v_max3_f32 v0, v0, v70, v71
	v_max3_f32 v0, v0, v72, v73
	s_waitcnt lgkmcnt(4)
	v_mfma_f32_32x32x16_bf16 v[34:49], v[174:177], v[222:225], v[34:49]
	ds_read_b64_tr_b16 v[222:223], v194 offset:0x2400
	ds_read_b64_tr_b16 v[224:225], v194 offset:0x2c00
	v_max3_f32 v0, v0, v74, v75
	v_max3_f32 v0, v0, v76, v77
	v_max3_f32 v0, v0, v78, v79
	v_mfma_f32_32x32x16_bf16 v[34:49], v[178:181], v[226:229], v[34:49]
	ds_read_b64_tr_b16 v[226:227], v194 offset:0x3400
	ds_read_b64_tr_b16 v[228:229], v194 offset:0x3c00
	v_max3_f32 v0, v0, v80, v81
	v_mov_b32_e32 v190, v0
	s_waitcnt lgkmcnt(4)
	v_mfma_f32_32x32x16_bf16 v[18:33], v[166:169], v[214:217], v[18:33]
	ds_read_b64_tr_b16 v[214:215], v194 offset:0x600
	ds_read_b64_tr_b16 v[216:217], v194 offset:0xe00
	v_permlane32_swap_b32_e32 v0, v190
	v_mfma_f32_32x32x16_bf16 v[18:33], v[170:173], v[218:221], v[18:33]
	ds_read_b64_tr_b16 v[218:219], v194 offset:0x1600
	ds_read_b64_tr_b16 v[220:221], v194 offset:0x1e00
	v_max_f32_e32 v0, v0, v190
	s_waitcnt lgkmcnt(4)
	v_mfma_f32_32x32x16_bf16 v[18:33], v[174:177], v[222:225], v[18:33]
	ds_read_b64_tr_b16 v[222:223], v194 offset:0x2600
	ds_read_b64_tr_b16 v[224:225], v194 offset:0x2e00
	v_sub_f32_e32 v190, v0, v210
	v_mfma_f32_32x32x16_bf16 v[18:33], v[178:181], v[226:229], v[18:33]
	ds_read_b64_tr_b16 v[226:227], v194 offset:0x3600
	ds_read_b64_tr_b16 v[228:229], v194 offset:0x3e00
	s_waitcnt lgkmcnt(4)
	v_mfma_f32_32x32x16_bf16 v[2:17], v[166:169], v[214:217], v[2:17]
	s_waitcnt vmcnt(2)
	v_add_u32_e32 v192, 0x10800, v206
	ds_write_b128 v207, v[154:157] offset:32768
	ds_write_b128 v207, v[158:161] offset:41472
	ds_write_b128 v192, v[162:165]
	v_mul_f32_e32 v190, 0x3d93cd3a, v190
	v_mfma_f32_32x32x16_bf16 v[2:17], v[170:173], v[218:221], v[2:17]
	s_mov_b32 s6, 0x41000000
	v_cmp_ge_f32_e32 vcc, s6, v190
	s_waitcnt lgkmcnt(3)
	v_mfma_f32_32x32x16_bf16 v[2:17], v[174:177], v[222:225], v[2:17]
	s_cmp_eq_u64 vcc, exec
	s_cselect_b64 s[6:7], -1, 0
	v_mfma_f32_32x32x16_bf16 v[2:17], v[178:181], v[226:229], v[2:17]
	s_barrier
	s_waitcnt vmcnt(0)
	ds_write_b128 v202, v[146:149]
	ds_write_b128 v203, v[150:153]
	s_and_b64 vcc, exec, s[6:7]
	s_cbranch_vccnz .Lfast1
	v_max_f32_e32 v0, v210, v0
	v_sub_f32_e32 v191, v210, v0
	v_mul_f32_e32 v191, 0x3dd53b94, v191
	v_exp_f32_e32 v213, v191
	v_mov_b32_e32 v210, v0
	v_cmp_gt_f32_e32 vcc, 1.0, v213
	s_cbranch_vccz .LBB0_414
	s_and_saveexec_b64 s[8:9], s[4:5]
	ds_write_b32 v195, v213 offset:128
	s_or_b64 exec, exec, s[8:9]
	s_waitcnt lgkmcnt(0)
	ds_read_b128 v[166:169], v198 offset:224
	ds_read_b128 v[170:173], v198 offset:192
	ds_read_b128 v[174:177], v198 offset:160
	ds_read_b128 v[178:181], v198 offset:128
	s_waitcnt lgkmcnt(3)
	v_pk_mul_f32 v[64:65], v[64:65], v[168:169]
	s_waitcnt lgkmcnt(2)
	v_pk_mul_f32 v[60:61], v[60:61], v[172:173]
	s_waitcnt lgkmcnt(1)
	v_pk_mul_f32 v[56:57], v[56:57], v[176:177]
	s_waitcnt lgkmcnt(0)
	v_pk_mul_f32 v[52:53], v[52:53], v[180:181]
	v_pk_mul_f32 v[62:63], v[62:63], v[166:167]
	v_pk_mul_f32 v[58:59], v[58:59], v[170:171]
	v_pk_mul_f32 v[54:55], v[54:55], v[174:175]
	v_pk_mul_f32 v[50:51], v[50:51], v[178:179]
	v_pk_mul_f32 v[48:49], v[48:49], v[168:169]
	v_pk_mul_f32 v[44:45], v[44:45], v[172:173]
	v_pk_mul_f32 v[40:41], v[40:41], v[176:177]
	v_pk_mul_f32 v[36:37], v[36:37], v[180:181]
	v_pk_mul_f32 v[46:47], v[46:47], v[166:167]
	v_pk_mul_f32 v[42:43], v[42:43], v[170:171]
	v_pk_mul_f32 v[38:39], v[38:39], v[174:175]
	v_pk_mul_f32 v[34:35], v[34:35], v[178:179]
	v_pk_mul_f32 v[32:33], v[32:33], v[168:169]
	v_pk_mul_f32 v[28:29], v[28:29], v[172:173]
	v_pk_mul_f32 v[24:25], v[24:25], v[176:177]
	v_pk_mul_f32 v[20:21], v[20:21], v[180:181]
	v_pk_mul_f32 v[30:31], v[30:31], v[166:167]
	v_pk_mul_f32 v[26:27], v[26:27], v[170:171]
	v_pk_mul_f32 v[22:23], v[22:23], v[174:175]
	v_pk_mul_f32 v[18:19], v[18:19], v[178:179]
	v_pk_mul_f32 v[16:17], v[16:17], v[168:169]
	v_pk_mul_f32 v[12:13], v[12:13], v[172:173]
	v_pk_mul_f32 v[8:9], v[8:9], v[176:177]
	v_pk_mul_f32 v[4:5], v[4:5], v[180:181]
	v_pk_mul_f32 v[14:15], v[14:15], v[166:167]
	v_pk_mul_f32 v[10:11], v[10:11], v[170:171]
	v_pk_mul_f32 v[6:7], v[6:7], v[174:175]
	v_pk_mul_f32 v[2:3], v[2:3], v[178:179]
	s_branch .LBB0_414
.Lfast1:
	v_mov_b32_e32 v213, 1.0
; __device__ __forceinline__ void partialSM(f32x16& p0, f32x16& p1, float& m_reg, float& mn, float& alpha) {
;     ...
;     const float mnL = -mn * C2;
; #pragma unroll
;     for (int r = 0; r < 16; ++r) p0[r] = fmaf(p0[r], C2, mnL);
; #pragma unroll
;     for (int r = 0; r < 16; ++r) p1[r] = fmaf(p1[r], C2, mnL);
.LBB0_414:
	v_mul_f32_e32 v181, 0xbdd53b94, v210
	v_fmamk_f32 v166, v82, 0x3dd53b94, v181
	v_fmamk_f32 v180, v83, 0x3dd53b94, v181
	v_fmamk_f32 v167, v84, 0x3dd53b94, v181
	v_fmamk_f32 v179, v85, 0x3dd53b94, v181
	v_fmamk_f32 v168, v86, 0x3dd53b94, v181
	v_fmamk_f32 v178, v87, 0x3dd53b94, v181
	v_fmamk_f32 v169, v88, 0x3dd53b94, v181
	v_fmamk_f32 v177, v89, 0x3dd53b94, v181
	v_fmamk_f32 v170, v90, 0x3dd53b94, v181
	v_fmamk_f32 v176, v91, 0x3dd53b94, v181
	v_fmamk_f32 v171, v92, 0x3dd53b94, v181
	v_fmamk_f32 v175, v93, 0x3dd53b94, v181
	v_fmamk_f32 v172, v94, 0x3dd53b94, v181
	v_fmamk_f32 v174, v95, 0x3dd53b94, v181
	v_fmamk_f32 v0, v96, 0x3dd53b94, v181
	v_fmamk_f32 v173, v97, 0x3dd53b94, v181
	v_fmamk_f32 v223, v66, 0x3dd53b94, v181
	v_fmamk_f32 v224, v67, 0x3dd53b94, v181
	v_fmamk_f32 v225, v68, 0x3dd53b94, v181
	v_fmamk_f32 v226, v69, 0x3dd53b94, v181
	v_fmamk_f32 v227, v70, 0x3dd53b94, v181
	v_fmamk_f32 v216, v71, 0x3dd53b94, v181
	v_fmamk_f32 v217, v72, 0x3dd53b94, v181
	v_fmamk_f32 v218, v73, 0x3dd53b94, v181
	v_fmamk_f32 v219, v74, 0x3dd53b94, v181
	v_fmamk_f32 v220, v75, 0x3dd53b94, v181
	v_fmamk_f32 v221, v76, 0x3dd53b94, v181
	v_fmamk_f32 v222, v77, 0x3dd53b94, v181
	v_fmamk_f32 v215, v78, 0x3dd53b94, v181
	v_fmamk_f32 v228, v79, 0x3dd53b94, v181
	v_fmamk_f32 v229, v80, 0x3dd53b94, v181
	v_fmac_f32_e32 v181, 0x3dd53b94, v81
	s_waitcnt lgkmcnt(0)
	s_barrier
; __device__ __forceinline__ void finishSM(f32x16& p0, f32x16& p1, float alpha, float& l_reg, bf16x8& pa0, bf16x8& pa1, bf16x8& pa2, bf16x8& pa3) {
; #pragma unroll
;     for (int r = 0; r < 16; ++r) p1[r] = __builtin_amdgcn_exp2f(p1[r]);
;     float ps = 0;
; #pragma unroll
;     for (int r = 0; r < 16; ++r) ps += p0[r];
; #pragma unroll
;     for (int r = 0; r < 16; ++r) ps += p1[r];
;     { auto rr = __builtin_amdgcn_permlane32_swap(__float_as_uint(ps), __float_as_uint(ps), false, false);
;       ps = __uint_as_float(rr[0]) + __uint_as_float(rr[1]); }
;     l_reg = l_reg * alpha + ps;
;     ...
;     PK4(p0, 0, pa0); PK4(p0, 8, pa1); PK4(p1, 0, pa2); PK4(p1, 8, pa3);
;     ...
; }
; template <int KB>
; __device__ __forceinline__ void qkt(f32x16& p0, f32x16& p1, const char* lds, int r32, int hi, const bf16x8* qr) {
;     p0 = f32x16{}; p1 = f32x16{};
;     const char* kb = lds + AO_K + KB * SHM_K + KSWZ(r32, hi * 16); const char* rb = lds + AO_R + KB * SHM_R + RSWZ(r32, hi * 16);
; #pragma unroll
;     for (int d0 = 0; d0 < 8; ++d0) { const char* a = kb + d0 * 32;
;         bf16x8 b0 = *reinterpret_cast<const bf16x8*>(a);
;         bf16x8 b1 = *reinterpret_cast<const bf16x8*>(a + 32 * KPITCH);
;         p0 = __builtin_amdgcn_mfma_f32_32x32x16_bf16(b0, qr[d0], p0, 0, 0, 0);
;         p1 = __builtin_amdgcn_mfma_f32_32x32x16_bf16(b1, qr[d0], p1, 0, 0, 0); }
; #pragma unroll
;     for (int d0 = 0; d0 < 4; ++d0) { const char* a = rb + d0 * 32;
;         bf16x8 b0 = *reinterpret_cast<const bf16x8*>(a);
;         bf16x8 b1 = *reinterpret_cast<const bf16x8*>(a + 32 * RPITCH);
;         p0 = __builtin_amdgcn_mfma_f32_32x32x16_bf16(b0, qr[8 + d0], p0, 0, 0, 0);
;         p1 = __builtin_amdgcn_mfma_f32_32x32x16_bf16(b1, qr[8 + d0], p1, 0, 0, 0); }
; }
	ds_read_b128 v[70:73], v200 offset:32768
	ds_read_b128 v[66:69], v200 offset:41472
	ds_read_b128 v[230:233], v200 offset:32800
	ds_read_b128 v[234:237], v200 offset:41504
	ds_read_b128 v[242:245], v200 offset:32832
	ds_read_b128 v[246:249], v200 offset:41536
	v_exp_f32_e32 v166, v166
	v_exp_f32_e32 v180, v180
	v_exp_f32_e32 v167, v167
	v_exp_f32_e32 v179, v179
	s_waitcnt lgkmcnt(4)
	v_mfma_f32_32x32x16_bf16 v[82:97], v[70:73], v[142:145], 0
	v_exp_f32_e32 v168, v168
	v_exp_f32_e32 v178, v178
	v_exp_f32_e32 v169, v169
	v_exp_f32_e32 v177, v177
	v_mfma_f32_32x32x16_bf16 v[66:81], v[66:69], v[142:145], 0
	v_exp_f32_e32 v170, v170
	v_exp_f32_e32 v176, v176
	v_exp_f32_e32 v171, v171
	v_exp_f32_e32 v175, v175
	s_waitcnt lgkmcnt(2)
	v_mfma_f32_32x32x16_bf16 v[66:81], v[234:237], v[138:141], v[66:81]
	v_exp_f32_e32 v172, v172
	v_exp_f32_e32 v174, v174
	v_exp_f32_e32 v173, v173
	v_exp_f32_e32 v0, v0
	v_mfma_f32_32x32x16_bf16 v[82:97], v[230:233], v[138:141], v[82:97]
	ds_read_b128 v[230:233], v200 offset:32864
	ds_read_b128 v[234:237], v200 offset:41568
	v_exp_f32_e32 v192, v225
	v_exp_f32_e32 v225, v215
	v_add_f32_e32 v215, v180, v166
	s_waitcnt lgkmcnt(2)
	v_mfma_f32_32x32x16_bf16 v[66:81], v[246:249], v[134:137], v[66:81]
	v_add_f32_e32 v215, v167, v215
	v_add_f32_e32 v215, v179, v215
	v_add_f32_e32 v215, v168, v215
	v_add_f32_e32 v215, v178, v215
	v_mfma_f32_32x32x16_bf16 v[82:97], v[242:245], v[134:137], v[82:97]
	ds_read_b128 v[242:245], v200 offset:32896
	ds_read_b128 v[246:249], v200 offset:41600
	v_add_f32_e32 v215, v169, v215
	v_add_f32_e32 v215, v177, v215
	v_add_f32_e32 v215, v170, v215
	v_add_f32_e32 v215, v176, v215
	s_waitcnt lgkmcnt(2)
	v_mfma_f32_32x32x16_bf16 v[66:81], v[234:237], v[130:133], v[66:81]
	v_add_f32_e32 v215, v171, v215
	v_add_f32_e32 v215, v175, v215
	v_exp_f32_e32 v190, v223
	v_add_f32_e32 v215, v172, v215
	v_mfma_f32_32x32x16_bf16 v[82:97], v[230:233], v[130:133], v[82:97]
	ds_read_b128 v[230:233], v200 offset:32928
	ds_read_b128 v[234:237], v200 offset:41632
	v_exp_f32_e32 v191, v224
	v_add_f32_e32 v215, v174, v215
	v_add_f32_e32 v215, v0, v215
	v_exp_f32_e32 v193, v226
	s_waitcnt lgkmcnt(2)
	v_mfma_f32_32x32x16_bf16 v[66:81], v[246:249], v[126:129], v[66:81]
	v_add_f32_e32 v215, v173, v215
	v_exp_f32_e32 v223, v227
	v_add_f32_e32 v215, v190, v215
	v_exp_f32_e32 v224, v216
	v_mfma_f32_32x32x16_bf16 v[82:97], v[242:245], v[126:129], v[82:97]
	ds_read_b128 v[242:245], v200 offset:32960
	ds_read_b128 v[246:249], v200 offset:41664
	v_add_f32_e32 v215, v191, v215
	v_exp_f32_e32 v217, v217
	v_add_f32_e32 v215, v192, v215
	v_exp_f32_e32 v218, v218
	s_waitcnt lgkmcnt(2)
	v_mfma_f32_32x32x16_bf16 v[66:81], v[234:237], v[122:125], v[66:81]
	v_add_f32_e32 v215, v193, v215
	v_exp_f32_e32 v219, v219
	v_add_f32_e32 v215, v223, v215
	v_mfma_f32_32x32x16_bf16 v[82:97], v[230:233], v[122:125], v[82:97]
	ds_read_b128 v[230:233], v200 offset:32992
	ds_read_b128 v[234:237], v200 offset:41696
	v_exp_f32_e32 v220, v220
	v_add_f32_e32 v215, v224, v215
	v_exp_f32_e32 v221, v221
	v_add_f32_e32 v215, v217, v215
	s_waitcnt lgkmcnt(2)
	v_mfma_f32_32x32x16_bf16 v[66:81], v[246:249], v[118:121], v[66:81]
	v_exp_f32_e32 v222, v222
	v_add_f32_e32 v215, v218, v215
	v_add_f32_e32 v215, v219, v215
	v_exp_f32_e32 v226, v228
	v_mfma_f32_32x32x16_bf16 v[82:97], v[242:245], v[118:121], v[82:97]
	ds_read_b128 v[242:245], v204
	ds_read_b128 v[246:249], v204 offset:4608
	v_add_f32_e32 v215, v220, v215
	v_exp_f32_e32 v227, v229
	v_add_f32_e32 v215, v221, v215
	v_exp_f32_e32 v181, v181
	s_waitcnt lgkmcnt(2)
	v_mfma_f32_32x32x16_bf16 v[66:81], v[234:237], v[110:113], v[66:81]
	v_add_f32_e32 v215, v222, v215
	v_add_f32_e32 v215, v225, v215
	v_add_f32_e32 v215, v226, v215
	v_add_f32_e32 v215, v227, v215
	v_mfma_f32_32x32x16_bf16 v[82:97], v[230:233], v[110:113], v[82:97]
	ds_read_b128 v[230:233], v204 offset:32
	ds_read_b128 v[234:237], v204 offset:4640
	v_add_f32_e32 v215, v181, v215
	v_mov_b32_e32 v216, v215
	v_cvt_pk_bf16_f32 v166, v166, v180
	v_cvt_pk_bf16_f32 v167, v167, v179
	s_waitcnt lgkmcnt(2)
	v_mfma_f32_32x32x16_bf16 v[66:81], v[246:249], v[114:117], v[66:81]
	v_cvt_pk_bf16_f32 v168, v168, v178
	v_cvt_pk_bf16_f32 v169, v169, v177
	v_cvt_pk_bf16_f32 v170, v170, v176
	v_cvt_pk_bf16_f32 v171, v171, v175
	v_mfma_f32_32x32x16_bf16 v[82:97], v[242:245], v[114:117], v[82:97]
	ds_read_b128 v[242:245], v204 offset:64
	ds_read_b128 v[246:249], v204 offset:4672
	v_cvt_pk_bf16_f32 v172, v172, v174
	v_cvt_pk_bf16_f32 v173, v0, v173
	v_cvt_pk_bf16_f32 v174, v190, v191
	v_cvt_pk_bf16_f32 v175, v192, v193
	s_waitcnt lgkmcnt(2)
	v_mfma_f32_32x32x16_bf16 v[82:97], v[230:233], v[106:109], v[82:97]
	v_cvt_pk_bf16_f32 v176, v223, v224
	v_cvt_pk_bf16_f32 v177, v217, v218
	v_cvt_pk_bf16_f32 v178, v219, v220
	v_cvt_pk_bf16_f32 v179, v221, v222
	v_mfma_f32_32x32x16_bf16 v[66:81], v[234:237], v[106:109], v[66:81]
	ds_read_b128 v[230:233], v204 offset:96
	ds_read_b128 v[234:237], v204 offset:4704
	v_cvt_pk_bf16_f32 v180, v225, v226
	v_cvt_pk_bf16_f32 v181, v227, v181
	v_permlane32_swap_b32_e32 v215, v216
	v_permlane32_swap_b32_e32 v166, v168
	s_waitcnt lgkmcnt(2)
	v_mfma_f32_32x32x16_bf16 v[82:97], v[242:245], v[102:105], v[82:97]
	v_permlane32_swap_b32_e32 v167, v169
	v_permlane32_swap_b32_e32 v170, v172
	v_permlane32_swap_b32_e32 v171, v173
	v_permlane32_swap_b32_e32 v174, v176
	v_mfma_f32_32x32x16_bf16 v[66:81], v[246:249], v[102:105], v[66:81]
	v_permlane32_swap_b32_e32 v175, v177
	v_permlane32_swap_b32_e32 v178, v180
	v_permlane32_swap_b32_e32 v179, v181
	s_waitcnt lgkmcnt(0)
	v_mfma_f32_32x32x16_bf16 v[82:97], v[230:233], v[98:101], v[82:97]
	v_mfma_f32_32x32x16_bf16 v[66:81], v[234:237], v[98:101], v[66:81]
	ds_read_b64_tr_b16 v[218:219], v194 offset:0x4000
	ds_read_b64_tr_b16 v[220:221], v194 offset:0x4800
	ds_read_b64_tr_b16 v[222:223], v194 offset:0x5000
	ds_read_b64_tr_b16 v[224:225], v194 offset:0x5800
	ds_read_b64_tr_b16 v[226:227], v194 offset:0x6000
	ds_read_b64_tr_b16 v[228:229], v194 offset:0x6800
	ds_read_b64_tr_b16 v[230:231], v194 offset:0x7000
	ds_read_b64_tr_b16 v[232:233], v194 offset:0x7800
	s_add_i32 s6, s82, 1
	s_cmp_lt_u32 s6, s83
	s_cselect_b64 s[90:91], -1, 0
	s_cmp_ge_u32 s6, s83
	s_cbranch_scc1 .LBB0_416
	s_add_u32 s8, s74, 0x1b98c000
	s_addc_u32 s9, s75, 0
	s_add_u32 s10, s74, 0x1b98e000
	s_addc_u32 s11, s75, 0
	s_add_u32 s12, s80, 0x18886000
	s_addc_u32 s13, s81, 0
	s_add_u32 s14, s74, 0x1d98c000
	s_addc_u32 s15, s75, 0
	s_add_u32 s16, s74, 0x1d98e000
	s_addc_u32 s17, s75, 0
	global_load_dwordx4 v[154:157], v201, s[8:9]
	global_load_dwordx4 v[158:161], v201, s[10:11]
	global_load_dwordx4 v[162:165], v199, s[12:13]
	global_load_dwordx4 v[146:149], v201, s[14:15]
	global_load_dwordx4 v[150:153], v201, s[16:17]

; __device__ __forceinline__ void partialSM(f32x16& p0, f32x16& p1, float& m_reg, float& mn, float& alpha) {
;     ...
;     if (__builtin_expect(__all((pmax - m_reg) * ASCALE <= ATHR), 1)) { mn = m_reg; alpha = 1.f; }
;     else { mn = fmaxf(m_reg, pmax); alpha = __builtin_amdgcn_exp2f((m_reg - mn) * C2); m_reg = mn; }
;     const float mnL = -mn * C2;
; #pragma unroll
;     for (int r = 0; r < 16; ++r) p0[r] = fmaf(p0[r], C2, mnL);
; #pragma unroll
;     for (int r = 0; r < 16; ++r) p1[r] = fmaf(p1[r], C2, mnL);
; __device__ __forceinline__ void attn_block(const ABlk& cur, char* lds, ASeam& Sm, const int tid, const int wv) {
;     ...
;     for (int t = 1; t + 1 < NT; t += 2) {
;         HALF_STEP(pB0, pB1, mnB, alB, pA0, pA1, alA, t, 1, 0, 0);
;         HALF_STEP(pA0, pA1, mnA, alA, pB0, pB1, alB, t + 1, 0, 1, 1);
.LBB0_420:
	s_waitcnt vmcnt(4)
	s_and_b64 vcc, exec, s[6:7]
	s_cbranch_vccnz .Lfast2
	v_max_f32_e32 v146, v210, v0
	v_sub_f32_e32 v0, v210, v146
	v_mul_f32_e32 v0, 0x3dd53b94, v0
	v_exp_f32_e32 v0, v0
	v_mov_b32_e32 v210, v146
	v_cmp_gt_f32_e32 vcc, 1.0, v0
	s_cbranch_vccz .LBB0_424
	s_and_saveexec_b64 s[8:9], s[4:5]
	ds_write_b32 v195, v0 offset:128
	s_or_b64 exec, exec, s[8:9]
	s_waitcnt lgkmcnt(0)
	s_waitcnt vmcnt(3)
	ds_read_b128 v[148:151], v198 offset:224
	s_waitcnt vmcnt(2)
	ds_read_b128 v[152:155], v198 offset:192
	s_waitcnt vmcnt(1)
	ds_read_b128 v[156:159], v198 offset:160
	s_waitcnt vmcnt(0)
	ds_read_b128 v[160:163], v198 offset:128
	s_waitcnt lgkmcnt(3)
	v_pk_mul_f32 v[64:65], v[64:65], v[150:151]
	s_waitcnt lgkmcnt(2)
	v_pk_mul_f32 v[60:61], v[60:61], v[154:155]
	s_waitcnt lgkmcnt(1)
	v_pk_mul_f32 v[56:57], v[56:57], v[158:159]
	s_waitcnt lgkmcnt(0)
	v_pk_mul_f32 v[52:53], v[52:53], v[162:163]
	v_pk_mul_f32 v[62:63], v[62:63], v[148:149]
	v_pk_mul_f32 v[58:59], v[58:59], v[152:153]
	v_pk_mul_f32 v[54:55], v[54:55], v[156:157]
	v_pk_mul_f32 v[50:51], v[50:51], v[160:161]
	v_pk_mul_f32 v[48:49], v[48:49], v[150:151]
	v_pk_mul_f32 v[44:45], v[44:45], v[154:155]
	v_pk_mul_f32 v[40:41], v[40:41], v[158:159]
	v_pk_mul_f32 v[36:37], v[36:37], v[162:163]
	v_pk_mul_f32 v[46:47], v[46:47], v[148:149]
	v_pk_mul_f32 v[42:43], v[42:43], v[152:153]
	v_pk_mul_f32 v[38:39], v[38:39], v[156:157]
	v_pk_mul_f32 v[34:35], v[34:35], v[160:161]
	v_pk_mul_f32 v[32:33], v[32:33], v[150:151]
	v_pk_mul_f32 v[28:29], v[28:29], v[154:155]
	v_pk_mul_f32 v[24:25], v[24:25], v[158:159]
	v_pk_mul_f32 v[20:21], v[20:21], v[162:163]
	v_pk_mul_f32 v[30:31], v[30:31], v[148:149]
	v_pk_mul_f32 v[26:27], v[26:27], v[152:153]
	v_pk_mul_f32 v[22:23], v[22:23], v[156:157]
	v_pk_mul_f32 v[18:19], v[18:19], v[160:161]
	v_pk_mul_f32 v[16:17], v[16:17], v[150:151]
	v_pk_mul_f32 v[12:13], v[12:13], v[154:155]
	v_pk_mul_f32 v[8:9], v[8:9], v[158:159]
	v_pk_mul_f32 v[4:5], v[4:5], v[162:163]
	v_pk_mul_f32 v[14:15], v[14:15], v[148:149]
	v_pk_mul_f32 v[10:11], v[10:11], v[152:153]
	v_pk_mul_f32 v[6:7], v[6:7], v[156:157]
	v_pk_mul_f32 v[2:3], v[2:3], v[160:161]
	s_branch .LBB0_424
.Lfast2:
	v_mov_b32_e32 v0, 1.0
.LBB0_424:
	s_waitcnt vmcnt(0)
	v_mul_f32_e32 v148, 0xbdd53b94, v210
	s_addk_i32 s70, 0x80
	v_fmamk_f32 v166, v82, 0x3dd53b94, v148
	v_fmamk_f32 v175, v83, 0x3dd53b94, v148
	v_fmamk_f32 v167, v84, 0x3dd53b94, v148
	v_fmamk_f32 v176, v85, 0x3dd53b94, v148
	v_fmamk_f32 v168, v86, 0x3dd53b94, v148
	v_fmamk_f32 v177, v87, 0x3dd53b94, v148
	v_fmamk_f32 v169, v88, 0x3dd53b94, v148
	v_fmamk_f32 v174, v89, 0x3dd53b94, v148
	v_fmamk_f32 v165, v90, 0x3dd53b94, v148
	v_fmamk_f32 v170, v91, 0x3dd53b94, v148
	v_fmamk_f32 v171, v92, 0x3dd53b94, v148
	v_fmamk_f32 v172, v93, 0x3dd53b94, v148
	v_fmamk_f32 v162, v94, 0x3dd53b94, v148
	v_fmamk_f32 v164, v95, 0x3dd53b94, v148
	v_fmamk_f32 v163, v96, 0x3dd53b94, v148
	v_fmamk_f32 v173, v97, 0x3dd53b94, v148
	s_add_u32 s76, s76, 0x8000
	s_addc_u32 s77, s77, 0
	v_pk_fma_f32 v[160:161], v[66:67], s[84:85], v[148:149] op_sel_hi:[1,0,0]
	v_add_f32_e32 v66, v211, v212
	s_add_u32 s88, s88, 0x4000
	v_fmac_f32_e32 v66, v208, v196
	v_add_f32_e32 v196, v215, v216
	s_addc_u32 s89, s89, 0
	s_add_i32 s82, s82, 2
	v_pk_fma_f32 v[158:159], v[68:69], s[84:85], v[148:149] op_sel_hi:[1,0,0]
	v_pk_fma_f32 v[154:155], v[70:71], s[84:85], v[148:149] op_sel_hi:[1,0,0]
	v_pk_fma_f32 v[150:151], v[72:73], s[84:85], v[148:149] op_sel_hi:[1,0,0]
	v_pk_fma_f32 v[146:147], v[74:75], s[84:85], v[148:149] op_sel_hi:[1,0,0]
	v_pk_fma_f32 v[156:157], v[76:77], s[84:85], v[148:149] op_sel_hi:[1,0,0]
	v_pk_fma_f32 v[152:153], v[78:79], s[84:85], v[148:149] op_sel_hi:[1,0,0]
	v_pk_fma_f32 v[148:149], v[80:81], s[84:85], v[148:149] op_sel_hi:[1,0,0]
	v_fmac_f32_e32 v196, v66, v213
	s_cmp_ge_u32 s82, s83
	v_add_u32_e32 v209, 0xffffff80, v209
	s_waitcnt lgkmcnt(0)
	s_barrier
	s_cbranch_scc1 .LBB0_426
	v_mov_b32_e32 v208, v0
	s_branch .LBB0_408
